# v26 + B1 stage-1 LoRA-input staging loop rewritten straight-line (all 27 loads per thread issued first)
# baseline (speedup 1.0000x reference)
; __device__ __forceinline__ void phase_a1(const P& p, const Ctx& c, int seg) {
;     ...
; #pragma unroll 1
;     for (int it = c.bid; it < MS / 8; it += c.G) {
.LBB0_240:
	v_mov_b32_e32 v170, v217
	v_readlane_b32 s47, v255, 2
	s_mov_b32 s45, s90
	s_cmp_lg_u32 s47, 0x100
	s_cbranch_scc1 .La1_noperm
	s_and_b32 s45, s90, 7
	s_lshl_b32 s45, s45, 5
	s_lshr_b32 s46, s90, 3
	s_or_b32 s45, s45, s46

; __device__ __forceinline__ void phase_a1(const P& p, const Ctx& c, int seg) {
;     ...
;             u32x2 nraw = *(const u32x2*)(P0 + (unsigned)(row0 * ML_W + n * 4));
; #pragma unroll 1
;             for (int tt = 0; tt < 8; ++tt) {
;                 const unsigned row = (unsigned)(row0 + tt);
;                 const u32x2 raw = nraw;
;                 if (tt + 1 < 8) nraw = *(const u32x2*)(P0 + (unsigned)((row + 1) * ML_W + n * 4));
.LBB0_271:
	v_lshl_add_u32 v4, s46, 15, v2
	s_waitcnt lgkmcnt(0)
	v_lshl_add_u64 v[98:99], v[4:5], 1, s[10:11]
	global_load_dwordx2 v[116:117], v[98:99], off
	v_lshlrev_b32_e32 v208, 2, v170
	v_ashrrev_i32_e32 v209, 31, v208
	v_lshlrev_b64 v[208:209], 2, v[208:209]
	v_lshl_add_u64 v[210:211], s[22:23], 0, v[208:209]
	global_load_dwordx4 v[218:221], v[210:211], off
	v_lshl_add_u64 v[210:211], s[20:21], 0, v[208:209]
	global_load_dwordx4 v[222:225], v[210:211], off
	v_lshl_add_u64 v[210:211], s[54:55], 0, v[208:209]
	global_load_dwordx4 v[226:229], v[210:211], off
	v_lshl_add_u64 v[210:211], s[56:57], 0, v[208:209]
	global_load_dwordx4 v[230:233], v[210:211], off
	v_lshl_add_u64 v[210:211], s[68:69], 0, v[208:209]
	global_load_dwordx4 v[234:237], v[210:211], off
	v_add_co_u32_e32 v210, vcc, 0x2000, v98
	s_nop 0
	v_addc_co_u32_e32 v211, vcc, 0, v99, vcc
	global_load_dwordx2 v[238:239], v[210:211], off
	v_add_co_u32_e32 v210, vcc, 0x2000, v210
	s_nop 0
	v_addc_co_u32_e32 v211, vcc, 0, v211, vcc
	global_load_dwordx2 v[240:241], v[210:211], off
	v_add_co_u32_e32 v210, vcc, 0x2000, v210
	s_nop 0
	v_addc_co_u32_e32 v211, vcc, 0, v211, vcc
	global_load_dwordx2 v[242:243], v[210:211], off
	v_add_co_u32_e32 v210, vcc, 0x2000, v210
	s_nop 0
	v_addc_co_u32_e32 v211, vcc, 0, v211, vcc
	global_load_dwordx2 v[244:245], v[210:211], off
	v_add_co_u32_e32 v210, vcc, 0x2000, v210
	s_nop 0
	v_addc_co_u32_e32 v211, vcc, 0, v211, vcc
	global_load_dwordx2 v[246:247], v[210:211], off
	v_add_co_u32_e32 v210, vcc, 0x2000, v210
	s_nop 0
	v_addc_co_u32_e32 v211, vcc, 0, v211, vcc
	global_load_dwordx2 v[248:249], v[210:211], off
	v_add_co_u32_e32 v210, vcc, 0x2000, v210
	s_nop 0
	v_addc_co_u32_e32 v211, vcc, 0, v211, vcc
	global_load_dwordx2 v[250:251], v[210:211], off
	s_waitcnt vmcnt(13)
	v_lshlrev_b32_e32 v100, 16, v102
	v_and_b32_e32 v101, 0xffff0000, v102
	v_lshlrev_b32_e32 v99, 16, v103
	v_and_b32_e32 v137, 0xffff0000, v103
	v_lshlrev_b32_e32 v102, 16, v104
	v_and_b32_e32 v103, 0xffff0000, v104
	v_lshlrev_b32_e32 v104, 16, v105
	v_and_b32_e32 v138, 0xffff0000, v105
	v_lshlrev_b32_e32 v118, 16, v106
	v_and_b32_e32 v119, 0xffff0000, v106
	v_lshlrev_b32_e32 v98, 16, v107
	v_and_b32_e32 v120, 0xffff0000, v107
	s_mov_b32 s8, -16
	v_mov_b32_e32 v4, v136
	v_mov_b32_e32 v106, v135
	v_mov_b32_e32 v139, v3
	s_waitcnt vmcnt(0)
	v_mov_b64_e32 v[108:109], v[116:117]
	s_branch .LBB0_273

; __device__ __forceinline__ float bf2f(bf16_t b) { return __uint_as_float(((unsigned)b) << 16); }
; __device__ __forceinline__ void phase_b1(const P& p, const Ctx& c, int seg) {
;     ...
;     for (int it = c.bid; it < MS / 16; it += c.G) {
;         const int r0 = it * 16, b = r0 >> 9, tl0 = r0 & 511;
;         __syncthreads();
;         for (int e = c.tid; e < 16 * 288; e += 512) { const int row = e / 288, cc = e % 288, col = 4608 + cc;
;             const float cur = bf2f(P1[(size_t)(r0 + row) * P1W + col]);
;             float prev = 0.f; if (tl0 + row > 0) prev = bf2f(P1[(size_t)(r0 + row - 1) * P1W + col]); else if (seg > 0) prev = bf2f(PTr[(size_t)b * RW_SHIFT + col]);
;             const float pv = cur + p.rw_mu[col] * (prev - cur);
.LBB0_715:
	s_lshl_b32 s35, s34, 4
	s_ashr_i32 s8, s34, 5
	s_and_b32 s9, s35, 0x1f0
	s_mul_hi_i32 s10, s8, 0x2640
	s_mul_i32 s11, s8, 0x2640
	s_barrier
	s_mov_b64 s[12:13], exec
	v_readlane_b32 s14, v255, 46
	v_readlane_b32 s15, v255, 47
	s_and_b64 s[14:15], s[12:13], s[14:15]
	s_mov_b64 exec, s[14:15]
	s_cbranch_execz .LBB0_728
	v_readlane_b32 s14, v255, 43
	s_add_u32 s14, s14, s11
	v_readlane_b32 s15, v255, 45
	s_addc_u32 s15, s15, s10
	s_mov_b32 s39, 0x38e38e39
	s_movk_i32 s40, 0x2800
	v_mov_b32_e32 v80, v138
	v_mul_hi_i32 v2, v80, s39
	v_lshrrev_b32_e32 v3, 31, v2
	v_ashrrev_i32_e32 v2, 6, v2
	v_add_u32_e32 v50, v2, v3
	v_mul_i32_i24_e32 v9, 0x120, v50
	v_sub_u32_e32 v60, v80, v9
	v_add_u32_e32 v12, s35, v50
	v_mov_b64_e32 v[2:3], s[78:79]
	v_add_u32_e32 v4, 0x1200, v60
	v_mad_i64_i32 v[2:3], s[56:57], v12, s40, v[2:3]
	v_lshl_add_u64 v[2:3], v[4:5], 1, v[2:3]
	global_load_ushort v20, v[2:3], off
	v_add_co_u32_e32 v8, vcc, 0xffffd800, v2
	s_nop 0
	v_addc_co_u32_e32 v9, vcc, -1, v3, vcc
	global_load_ushort v30, v[8:9], off
	v_lshl_add_u64 v[8:9], v[4:5], 2, s[68:69]
	global_load_dword v40, v[8:9], off
	v_add_u32_e32 v81, 512, v138
	v_mul_hi_i32 v2, v81, s39
	v_lshrrev_b32_e32 v3, 31, v2
	v_ashrrev_i32_e32 v2, 6, v2
	v_add_u32_e32 v51, v2, v3
	v_mul_i32_i24_e32 v9, 0x120, v51
	v_sub_u32_e32 v61, v81, v9
	v_add_u32_e32 v12, s35, v51
	v_mov_b64_e32 v[2:3], s[78:79]
	v_add_u32_e32 v4, 0x1200, v61
	v_mad_i64_i32 v[2:3], s[56:57], v12, s40, v[2:3]
	v_lshl_add_u64 v[2:3], v[4:5], 1, v[2:3]
	global_load_ushort v21, v[2:3], off
	v_add_co_u32_e32 v8, vcc, 0xffffd800, v2
	s_nop 0
	v_addc_co_u32_e32 v9, vcc, -1, v3, vcc
	global_load_ushort v31, v[8:9], off
	v_lshl_add_u64 v[8:9], v[4:5], 2, s[68:69]
	global_load_dword v41, v[8:9], off
	v_add_u32_e32 v82, 1024, v138
	v_mul_hi_i32 v2, v82, s39
	v_lshrrev_b32_e32 v3, 31, v2
	v_ashrrev_i32_e32 v2, 6, v2
	v_add_u32_e32 v52, v2, v3
	v_mul_i32_i24_e32 v9, 0x120, v52
	v_sub_u32_e32 v62, v82, v9
	v_add_u32_e32 v12, s35, v52
	v_mov_b64_e32 v[2:3], s[78:79]
	v_add_u32_e32 v4, 0x1200, v62
	v_mad_i64_i32 v[2:3], s[56:57], v12, s40, v[2:3]
	v_lshl_add_u64 v[2:3], v[4:5], 1, v[2:3]
	global_load_ushort v22, v[2:3], off
	v_add_co_u32_e32 v8, vcc, 0xffffd800, v2
	s_nop 0
	v_addc_co_u32_e32 v9, vcc, -1, v3, vcc
	global_load_ushort v32, v[8:9], off
	v_lshl_add_u64 v[8:9], v[4:5], 2, s[68:69]
	global_load_dword v42, v[8:9], off
	v_add_u32_e32 v83, 1536, v138
	v_mul_hi_i32 v2, v83, s39
	v_lshrrev_b32_e32 v3, 31, v2
	v_ashrrev_i32_e32 v2, 6, v2
	v_add_u32_e32 v53, v2, v3
	v_mul_i32_i24_e32 v9, 0x120, v53
	v_sub_u32_e32 v63, v83, v9
	v_add_u32_e32 v12, s35, v53
	v_mov_b64_e32 v[2:3], s[78:79]
	v_add_u32_e32 v4, 0x1200, v63
	v_mad_i64_i32 v[2:3], s[56:57], v12, s40, v[2:3]
	v_lshl_add_u64 v[2:3], v[4:5], 1, v[2:3]
	global_load_ushort v23, v[2:3], off
	v_add_co_u32_e32 v8, vcc, 0xffffd800, v2
	s_nop 0
	v_addc_co_u32_e32 v9, vcc, -1, v3, vcc
	global_load_ushort v33, v[8:9], off
	v_lshl_add_u64 v[8:9], v[4:5], 2, s[68:69]
	global_load_dword v43, v[8:9], off
	v_add_u32_e32 v84, 2048, v138
	v_mul_hi_i32 v2, v84, s39
	v_lshrrev_b32_e32 v3, 31, v2
	v_ashrrev_i32_e32 v2, 6, v2
	v_add_u32_e32 v54, v2, v3
	v_mul_i32_i24_e32 v9, 0x120, v54
	v_sub_u32_e32 v64, v84, v9
	v_add_u32_e32 v12, s35, v54
	v_mov_b64_e32 v[2:3], s[78:79]
	v_add_u32_e32 v4, 0x1200, v64
	v_mad_i64_i32 v[2:3], s[56:57], v12, s40, v[2:3]
	v_lshl_add_u64 v[2:3], v[4:5], 1, v[2:3]
	global_load_ushort v24, v[2:3], off
	v_add_co_u32_e32 v8, vcc, 0xffffd800, v2
	s_nop 0
	v_addc_co_u32_e32 v9, vcc, -1, v3, vcc
	global_load_ushort v34, v[8:9], off
	v_lshl_add_u64 v[8:9], v[4:5], 2, s[68:69]
	global_load_dword v44, v[8:9], off
	v_add_u32_e32 v85, 2560, v138
	v_mul_hi_i32 v2, v85, s39
	v_lshrrev_b32_e32 v3, 31, v2
	v_ashrrev_i32_e32 v2, 6, v2
	v_add_u32_e32 v55, v2, v3
	v_mul_i32_i24_e32 v9, 0x120, v55
	v_sub_u32_e32 v65, v85, v9
	v_add_u32_e32 v12, s35, v55
	v_mov_b64_e32 v[2:3], s[78:79]
	v_add_u32_e32 v4, 0x1200, v65
	v_mad_i64_i32 v[2:3], s[56:57], v12, s40, v[2:3]
	v_lshl_add_u64 v[2:3], v[4:5], 1, v[2:3]
	global_load_ushort v25, v[2:3], off
	v_add_co_u32_e32 v8, vcc, 0xffffd800, v2
	s_nop 0
	v_addc_co_u32_e32 v9, vcc, -1, v3, vcc
	global_load_ushort v35, v[8:9], off
	v_lshl_add_u64 v[8:9], v[4:5], 2, s[68:69]
	global_load_dword v45, v[8:9], off
	v_add_u32_e32 v86, 3072, v138
	v_mul_hi_i32 v2, v86, s39
	v_lshrrev_b32_e32 v3, 31, v2
	v_ashrrev_i32_e32 v2, 6, v2
	v_add_u32_e32 v56, v2, v3
	v_mul_i32_i24_e32 v9, 0x120, v56
	v_sub_u32_e32 v66, v86, v9
	v_add_u32_e32 v12, s35, v56
	v_mov_b64_e32 v[2:3], s[78:79]
	v_add_u32_e32 v4, 0x1200, v66
	v_mad_i64_i32 v[2:3], s[56:57], v12, s40, v[2:3]
	v_lshl_add_u64 v[2:3], v[4:5], 1, v[2:3]
	global_load_ushort v26, v[2:3], off
	v_add_co_u32_e32 v8, vcc, 0xffffd800, v2
	s_nop 0
	v_addc_co_u32_e32 v9, vcc, -1, v3, vcc
	global_load_ushort v36, v[8:9], off
	v_lshl_add_u64 v[8:9], v[4:5], 2, s[68:69]
	global_load_dword v46, v[8:9], off
	v_add_u32_e32 v87, 3584, v138
	v_mul_hi_i32 v2, v87, s39
	v_lshrrev_b32_e32 v3, 31, v2
	v_ashrrev_i32_e32 v2, 6, v2
	v_add_u32_e32 v57, v2, v3
	v_mul_i32_i24_e32 v9, 0x120, v57
	v_sub_u32_e32 v67, v87, v9
	v_add_u32_e32 v12, s35, v57
	v_mov_b64_e32 v[2:3], s[78:79]
	v_add_u32_e32 v4, 0x1200, v67
	v_mad_i64_i32 v[2:3], s[56:57], v12, s40, v[2:3]
	v_lshl_add_u64 v[2:3], v[4:5], 1, v[2:3]
	global_load_ushort v27, v[2:3], off
	v_add_co_u32_e32 v8, vcc, 0xffffd800, v2
	s_nop 0
	v_addc_co_u32_e32 v9, vcc, -1, v3, vcc
	global_load_ushort v37, v[8:9], off
	v_lshl_add_u64 v[8:9], v[4:5], 2, s[68:69]
	global_load_dword v47, v[8:9], off
	v_add_u32_e32 v88, 4096, v138
	v_mul_hi_i32 v2, v88, s39
	v_lshrrev_b32_e32 v3, 31, v2
	v_ashrrev_i32_e32 v2, 6, v2
	v_add_u32_e32 v58, v2, v3
	v_mul_i32_i24_e32 v9, 0x120, v58
	v_sub_u32_e32 v68, v88, v9
	v_add_u32_e32 v12, s35, v58
	v_mov_b64_e32 v[2:3], s[78:79]
	v_add_u32_e32 v4, 0x1200, v68
	v_mad_i64_i32 v[2:3], s[56:57], v12, s40, v[2:3]
	v_lshl_add_u64 v[2:3], v[4:5], 1, v[2:3]
	global_load_ushort v28, v[2:3], off
	v_add_co_u32_e32 v8, vcc, 0xffffd800, v2
	s_nop 0
	v_addc_co_u32_e32 v9, vcc, -1, v3, vcc
	global_load_ushort v38, v[8:9], off
	v_lshl_add_u64 v[8:9], v[4:5], 2, s[68:69]
	global_load_dword v48, v[8:9], off
	s_cmp_lg_u32 s9, 0
	s_cbranch_scc1 .Lb1s_nosp_ld
	v_readlane_b32 s20, v255, 41
	v_readlane_b32 s21, v255, 42
	s_cmp_eq_u64 s[20:21], 0
	s_cbranch_scc1 .Lb1s_nosp_ld
	v_cmp_eq_u32_e32 vcc, 0, v50
	s_and_saveexec_b64 s[16:17], vcc
	v_add_u32_e32 v4, 0x1200, v60
	v_lshl_add_u64 v[2:3], v[4:5], 1, s[14:15]
	global_load_ushort v70, v[2:3], off
	s_mov_b64 exec, s[16:17]
; __device__ __forceinline__ bf16_t f2bf(float f) { const __bf16 r = (__bf16)f; bf16_t u; __builtin_memcpy(&u, &r, 2); return u; }
; __device__ __forceinline__ float bf2f(bf16_t b) { return __uint_as_float(((unsigned)b) << 16); }
; __device__ __forceinline__ float sigmoidf_(float x) { return frcp(1.0f + __expf(-x)); }
; __device__ __forceinline__ void phase_b1(const P& p, const Ctx& c, int seg) {
;     ...
;         for (int e = c.tid; e < 16 * 288; e += 512) { const int row = e / 288, cc = e % 288, col = 4608 + cc;
;             const float cur = bf2f(P1[(size_t)(r0 + row) * P1W + col]);
;             float prev = 0.f; if (tl0 + row > 0) prev = bf2f(P1[(size_t)(r0 + row - 1) * P1W + col]); else if (seg > 0) prev = bf2f(PTr[(size_t)b * RW_SHIFT + col]);
;             const float pv = cur + p.rw_mu[col] * (prev - cur);
;             const float f = cc < 64 ? (1.0f - 2.0f / (1.0f + __expf(2.0f * pv)))   : (cc < 160 ? pv : sigmoidf_(pv));
;             XA[row * 296 + cc] = f2bf(f); }
.Lb1s_nosp_ld:
	s_waitcnt vmcnt(0)
	s_cmp_lg_u32 s9, 0
	s_cbranch_scc1 .Lb1s_nosp_fix
	v_cmp_eq_u32_e32 vcc, 0, v50
	s_and_saveexec_b64 s[16:17], vcc
	v_mov_b32_e32 v30, 0
	v_readlane_b32 s20, v255, 41
	v_readlane_b32 s21, v255, 42
	s_cmp_eq_u64 s[20:21], 0
	s_cbranch_scc1 .Lb1s_sp_zero
	v_mov_b32_e32 v30, v70
.Lb1s_sp_zero:
	s_mov_b64 exec, s[16:17]
.Lb1s_nosp_fix:
	s_movk_i32 s40, 0xa0
	v_lshlrev_b32_e32 v2, 16, v20
	v_lshlrev_b32_e32 v12, 16, v30
	v_sub_f32_e32 v4, v12, v2
	v_fmac_f32_e32 v2, v4, v40
	v_cmp_lt_i32_e32 vcc, 63, v60
	s_mov_b64 s[20:21], exec
	s_and_b64 exec, exec, vcc
	s_cbranch_execz .Lb1s_t0
	v_mul_f32_e32 v3, 0xbfb8aa3b, v2
	v_exp_f32_e32 v3, v3
	v_cmp_gt_u32_e32 vcc, s40, v60
	v_add_f32_e32 v3, 1.0, v3
	v_rcp_f32_e32 v3, v3
	s_nop 0
	v_cndmask_b32_e32 v3, v3, v2, vcc
.Lb1s_t0:
	s_andn2_b64 exec, s[20:21], exec
	s_cbranch_execz .Lb1s_j0
	v_add_f32_e32 v2, v2, v2
	v_mul_f32_e32 v2, 0x3fb8aa3b, v2
	v_exp_f32_e32 v2, v2
	s_nop 0
	v_add_f32_e32 v2, 1.0, v2
	v_div_scale_f32 v3, s[56:57], v2, v2, 2.0
	v_rcp_f32_e32 v4, v3
	v_div_scale_f32 v10, vcc, 2.0, v2, 2.0
	v_fma_f32 v11, -v3, v4, 1.0
	v_fmac_f32_e32 v4, v11, v4
	v_mul_f32_e32 v11, v10, v4
	v_fma_f32 v12, -v3, v11, v10
	v_fmac_f32_e32 v11, v12, v4
	v_fma_f32 v3, -v3, v11, v10
	v_div_fmas_f32 v3, v3, v4, v11
	v_div_fixup_f32 v2, v3, v2, 2.0
	v_sub_f32_e32 v3, 1.0, v2
.Lb1s_j0:
	s_mov_b64 exec, s[20:21]
	v_cvt_pk_bf16_f32 v2, v3, s0
	v_lshlrev_b32_e32 v4, 4, v50
	v_lshl_add_u32 v4, v80, 1, v4
	ds_write_b16 v4, v2
	v_lshlrev_b32_e32 v2, 16, v21
	v_lshlrev_b32_e32 v12, 16, v31
	v_sub_f32_e32 v4, v12, v2
	v_fmac_f32_e32 v2, v4, v41
	v_cmp_lt_i32_e32 vcc, 63, v61
	s_mov_b64 s[20:21], exec
	s_and_b64 exec, exec, vcc
	s_cbranch_execz .Lb1s_t1
	v_mul_f32_e32 v3, 0xbfb8aa3b, v2
	v_exp_f32_e32 v3, v3
	v_cmp_gt_u32_e32 vcc, s40, v61
	v_add_f32_e32 v3, 1.0, v3
	v_rcp_f32_e32 v3, v3
	s_nop 0
	v_cndmask_b32_e32 v3, v3, v2, vcc

; __device__ __forceinline__ bf16_t f2bf(float f) { const __bf16 r = (__bf16)f; bf16_t u; __builtin_memcpy(&u, &r, 2); return u; }
; __device__ __forceinline__ float bf2f(bf16_t b) { return __uint_as_float(((unsigned)b) << 16); }
; __device__ __forceinline__ float sigmoidf_(float x) { return frcp(1.0f + __expf(-x)); }
; __device__ __forceinline__ void phase_b1(const P& p, const Ctx& c, int seg) {
;     ...
;         for (int e = c.tid; e < 16 * 288; e += 512) { const int row = e / 288, cc = e % 288, col = 4608 + cc;
;             const float cur = bf2f(P1[(size_t)(r0 + row) * P1W + col]);
;             float prev = 0.f; if (tl0 + row > 0) prev = bf2f(P1[(size_t)(r0 + row - 1) * P1W + col]); else if (seg > 0) prev = bf2f(PTr[(size_t)b * RW_SHIFT + col]);
;             const float pv = cur + p.rw_mu[col] * (prev - cur);
;             const float f = cc < 64 ? (1.0f - 2.0f / (1.0f + __expf(2.0f * pv)))   : (cc < 160 ? pv : sigmoidf_(pv));
;             XA[row * 296 + cc] = f2bf(f); }
.Lb1s_j1:
	s_mov_b64 exec, s[20:21]
	v_cvt_pk_bf16_f32 v2, v3, s0
	v_lshlrev_b32_e32 v4, 4, v51
	v_lshl_add_u32 v4, v81, 1, v4
	ds_write_b16 v4, v2
	v_lshlrev_b32_e32 v2, 16, v22
	v_lshlrev_b32_e32 v12, 16, v32
	v_sub_f32_e32 v4, v12, v2
	v_fmac_f32_e32 v2, v4, v42
	v_cmp_lt_i32_e32 vcc, 63, v62
	s_mov_b64 s[20:21], exec
	s_and_b64 exec, exec, vcc
	s_cbranch_execz .Lb1s_t2
	v_mul_f32_e32 v3, 0xbfb8aa3b, v2
	v_exp_f32_e32 v3, v3
	v_cmp_gt_u32_e32 vcc, s40, v62
	v_add_f32_e32 v3, 1.0, v3
	v_rcp_f32_e32 v3, v3
	s_nop 0
	v_cndmask_b32_e32 v3, v3, v2, vcc

; __device__ __forceinline__ bf16_t f2bf(float f) { const __bf16 r = (__bf16)f; bf16_t u; __builtin_memcpy(&u, &r, 2); return u; }
; __device__ __forceinline__ float bf2f(bf16_t b) { return __uint_as_float(((unsigned)b) << 16); }
; __device__ __forceinline__ float sigmoidf_(float x) { return frcp(1.0f + __expf(-x)); }
; __device__ __forceinline__ void phase_b1(const P& p, const Ctx& c, int seg) {
;     ...
;         for (int e = c.tid; e < 16 * 288; e += 512) { const int row = e / 288, cc = e % 288, col = 4608 + cc;
;             const float cur = bf2f(P1[(size_t)(r0 + row) * P1W + col]);
;             float prev = 0.f; if (tl0 + row > 0) prev = bf2f(P1[(size_t)(r0 + row - 1) * P1W + col]); else if (seg > 0) prev = bf2f(PTr[(size_t)b * RW_SHIFT + col]);
;             const float pv = cur + p.rw_mu[col] * (prev - cur);
;             const float f = cc < 64 ? (1.0f - 2.0f / (1.0f + __expf(2.0f * pv)))   : (cc < 160 ? pv : sigmoidf_(pv));
;             XA[row * 296 + cc] = f2bf(f); }
.Lb1s_j2:
	s_mov_b64 exec, s[20:21]
	v_cvt_pk_bf16_f32 v2, v3, s0
	v_lshlrev_b32_e32 v4, 4, v52
	v_lshl_add_u32 v4, v82, 1, v4
	ds_write_b16 v4, v2
	v_lshlrev_b32_e32 v2, 16, v23
	v_lshlrev_b32_e32 v12, 16, v33
	v_sub_f32_e32 v4, v12, v2
	v_fmac_f32_e32 v2, v4, v43
	v_cmp_lt_i32_e32 vcc, 63, v63
	s_mov_b64 s[20:21], exec
	s_and_b64 exec, exec, vcc
	s_cbranch_execz .Lb1s_t3
	v_mul_f32_e32 v3, 0xbfb8aa3b, v2
	v_exp_f32_e32 v3, v3
	v_cmp_gt_u32_e32 vcc, s40, v63
	v_add_f32_e32 v3, 1.0, v3
	v_rcp_f32_e32 v3, v3
	s_nop 0
	v_cndmask_b32_e32 v3, v3, v2, vcc

; __device__ __forceinline__ bf16_t f2bf(float f) { const __bf16 r = (__bf16)f; bf16_t u; __builtin_memcpy(&u, &r, 2); return u; }
; __device__ __forceinline__ float bf2f(bf16_t b) { return __uint_as_float(((unsigned)b) << 16); }
; __device__ __forceinline__ float sigmoidf_(float x) { return frcp(1.0f + __expf(-x)); }
; __device__ __forceinline__ void phase_b1(const P& p, const Ctx& c, int seg) {
;     ...
;         for (int e = c.tid; e < 16 * 288; e += 512) { const int row = e / 288, cc = e % 288, col = 4608 + cc;
;             const float cur = bf2f(P1[(size_t)(r0 + row) * P1W + col]);
;             float prev = 0.f; if (tl0 + row > 0) prev = bf2f(P1[(size_t)(r0 + row - 1) * P1W + col]); else if (seg > 0) prev = bf2f(PTr[(size_t)b * RW_SHIFT + col]);
;             const float pv = cur + p.rw_mu[col] * (prev - cur);
;             const float f = cc < 64 ? (1.0f - 2.0f / (1.0f + __expf(2.0f * pv)))   : (cc < 160 ? pv : sigmoidf_(pv));
;             XA[row * 296 + cc] = f2bf(f); }
.Lb1s_j3:
	s_mov_b64 exec, s[20:21]
	v_cvt_pk_bf16_f32 v2, v3, s0
	v_lshlrev_b32_e32 v4, 4, v53
	v_lshl_add_u32 v4, v83, 1, v4
	ds_write_b16 v4, v2
	v_lshlrev_b32_e32 v2, 16, v24
	v_lshlrev_b32_e32 v12, 16, v34
	v_sub_f32_e32 v4, v12, v2
	v_fmac_f32_e32 v2, v4, v44
	v_cmp_lt_i32_e32 vcc, 63, v64
	s_mov_b64 s[20:21], exec
	s_and_b64 exec, exec, vcc
	s_cbranch_execz .Lb1s_t4
	v_mul_f32_e32 v3, 0xbfb8aa3b, v2
	v_exp_f32_e32 v3, v3
	v_cmp_gt_u32_e32 vcc, s40, v64
	v_add_f32_e32 v3, 1.0, v3
	v_rcp_f32_e32 v3, v3
	s_nop 0
	v_cndmask_b32_e32 v3, v3, v2, vcc

; __device__ __forceinline__ bf16_t f2bf(float f) { const __bf16 r = (__bf16)f; bf16_t u; __builtin_memcpy(&u, &r, 2); return u; }
; __device__ __forceinline__ float bf2f(bf16_t b) { return __uint_as_float(((unsigned)b) << 16); }
; __device__ __forceinline__ float sigmoidf_(float x) { return frcp(1.0f + __expf(-x)); }
; __device__ __forceinline__ void phase_b1(const P& p, const Ctx& c, int seg) {
;     ...
;         for (int e = c.tid; e < 16 * 288; e += 512) { const int row = e / 288, cc = e % 288, col = 4608 + cc;
;             const float cur = bf2f(P1[(size_t)(r0 + row) * P1W + col]);
;             float prev = 0.f; if (tl0 + row > 0) prev = bf2f(P1[(size_t)(r0 + row - 1) * P1W + col]); else if (seg > 0) prev = bf2f(PTr[(size_t)b * RW_SHIFT + col]);
;             const float pv = cur + p.rw_mu[col] * (prev - cur);
;             const float f = cc < 64 ? (1.0f - 2.0f / (1.0f + __expf(2.0f * pv)))   : (cc < 160 ? pv : sigmoidf_(pv));
;             XA[row * 296 + cc] = f2bf(f); }
.Lb1s_j4:
	s_mov_b64 exec, s[20:21]
	v_cvt_pk_bf16_f32 v2, v3, s0
	v_lshlrev_b32_e32 v4, 4, v54
	v_lshl_add_u32 v4, v84, 1, v4
	ds_write_b16 v4, v2
	v_lshlrev_b32_e32 v2, 16, v25
	v_lshlrev_b32_e32 v12, 16, v35
	v_sub_f32_e32 v4, v12, v2
	v_fmac_f32_e32 v2, v4, v45
	v_cmp_lt_i32_e32 vcc, 63, v65
	s_mov_b64 s[20:21], exec
	s_and_b64 exec, exec, vcc
	s_cbranch_execz .Lb1s_t5
	v_mul_f32_e32 v3, 0xbfb8aa3b, v2
	v_exp_f32_e32 v3, v3
	v_cmp_gt_u32_e32 vcc, s40, v65
	v_add_f32_e32 v3, 1.0, v3
	v_rcp_f32_e32 v3, v3
	s_nop 0
	v_cndmask_b32_e32 v3, v3, v2, vcc

; __device__ __forceinline__ bf16_t f2bf(float f) { const __bf16 r = (__bf16)f; bf16_t u; __builtin_memcpy(&u, &r, 2); return u; }
; __device__ __forceinline__ float bf2f(bf16_t b) { return __uint_as_float(((unsigned)b) << 16); }
; __device__ __forceinline__ float sigmoidf_(float x) { return frcp(1.0f + __expf(-x)); }
; __device__ __forceinline__ void phase_b1(const P& p, const Ctx& c, int seg) {
;     ...
;         for (int e = c.tid; e < 16 * 288; e += 512) { const int row = e / 288, cc = e % 288, col = 4608 + cc;
;             const float cur = bf2f(P1[(size_t)(r0 + row) * P1W + col]);
;             float prev = 0.f; if (tl0 + row > 0) prev = bf2f(P1[(size_t)(r0 + row - 1) * P1W + col]); else if (seg > 0) prev = bf2f(PTr[(size_t)b * RW_SHIFT + col]);
;             const float pv = cur + p.rw_mu[col] * (prev - cur);
;             const float f = cc < 64 ? (1.0f - 2.0f / (1.0f + __expf(2.0f * pv)))   : (cc < 160 ? pv : sigmoidf_(pv));
;             XA[row * 296 + cc] = f2bf(f); }
.Lb1s_j5:
	s_mov_b64 exec, s[20:21]
	v_cvt_pk_bf16_f32 v2, v3, s0
	v_lshlrev_b32_e32 v4, 4, v55
	v_lshl_add_u32 v4, v85, 1, v4
	ds_write_b16 v4, v2
	v_lshlrev_b32_e32 v2, 16, v26
	v_lshlrev_b32_e32 v12, 16, v36
	v_sub_f32_e32 v4, v12, v2
	v_fmac_f32_e32 v2, v4, v46
	v_cmp_lt_i32_e32 vcc, 63, v66
	s_mov_b64 s[20:21], exec
	s_and_b64 exec, exec, vcc
	s_cbranch_execz .Lb1s_t6
	v_mul_f32_e32 v3, 0xbfb8aa3b, v2
	v_exp_f32_e32 v3, v3
	v_cmp_gt_u32_e32 vcc, s40, v66
	v_add_f32_e32 v3, 1.0, v3
	v_rcp_f32_e32 v3, v3
	s_nop 0
	v_cndmask_b32_e32 v3, v3, v2, vcc

; __device__ __forceinline__ bf16_t f2bf(float f) { const __bf16 r = (__bf16)f; bf16_t u; __builtin_memcpy(&u, &r, 2); return u; }
; __device__ __forceinline__ float bf2f(bf16_t b) { return __uint_as_float(((unsigned)b) << 16); }
; __device__ __forceinline__ float sigmoidf_(float x) { return frcp(1.0f + __expf(-x)); }
; __device__ __forceinline__ void phase_b1(const P& p, const Ctx& c, int seg) {
;     ...
;         for (int e = c.tid; e < 16 * 288; e += 512) { const int row = e / 288, cc = e % 288, col = 4608 + cc;
;             const float cur = bf2f(P1[(size_t)(r0 + row) * P1W + col]);
;             float prev = 0.f; if (tl0 + row > 0) prev = bf2f(P1[(size_t)(r0 + row - 1) * P1W + col]); else if (seg > 0) prev = bf2f(PTr[(size_t)b * RW_SHIFT + col]);
;             const float pv = cur + p.rw_mu[col] * (prev - cur);
;             const float f = cc < 64 ? (1.0f - 2.0f / (1.0f + __expf(2.0f * pv)))   : (cc < 160 ? pv : sigmoidf_(pv));
;             XA[row * 296 + cc] = f2bf(f); }
.Lb1s_j6:
	s_mov_b64 exec, s[20:21]
	v_cvt_pk_bf16_f32 v2, v3, s0
	v_lshlrev_b32_e32 v4, 4, v56
	v_lshl_add_u32 v4, v86, 1, v4
	ds_write_b16 v4, v2
	v_lshlrev_b32_e32 v2, 16, v27
	v_lshlrev_b32_e32 v12, 16, v37
	v_sub_f32_e32 v4, v12, v2
	v_fmac_f32_e32 v2, v4, v47
	v_cmp_lt_i32_e32 vcc, 63, v67
	s_mov_b64 s[20:21], exec
	s_and_b64 exec, exec, vcc
	s_cbranch_execz .Lb1s_t7
	v_mul_f32_e32 v3, 0xbfb8aa3b, v2
	v_exp_f32_e32 v3, v3
	v_cmp_gt_u32_e32 vcc, s40, v67
	v_add_f32_e32 v3, 1.0, v3
	v_rcp_f32_e32 v3, v3
	s_nop 0
	v_cndmask_b32_e32 v3, v3, v2, vcc

; __device__ __forceinline__ bf16_t f2bf(float f) { const __bf16 r = (__bf16)f; bf16_t u; __builtin_memcpy(&u, &r, 2); return u; }
; __device__ __forceinline__ float bf2f(bf16_t b) { return __uint_as_float(((unsigned)b) << 16); }
; __device__ __forceinline__ float sigmoidf_(float x) { return frcp(1.0f + __expf(-x)); }
; __device__ __forceinline__ void phase_b1(const P& p, const Ctx& c, int seg) {
;     ...
;         for (int e = c.tid; e < 16 * 288; e += 512) { const int row = e / 288, cc = e % 288, col = 4608 + cc;
;             const float cur = bf2f(P1[(size_t)(r0 + row) * P1W + col]);
;             float prev = 0.f; if (tl0 + row > 0) prev = bf2f(P1[(size_t)(r0 + row - 1) * P1W + col]); else if (seg > 0) prev = bf2f(PTr[(size_t)b * RW_SHIFT + col]);
;             const float pv = cur + p.rw_mu[col] * (prev - cur);
;             const float f = cc < 64 ? (1.0f - 2.0f / (1.0f + __expf(2.0f * pv)))   : (cc < 160 ? pv : sigmoidf_(pv));
;             XA[row * 296 + cc] = f2bf(f); }
.Lb1s_j7:
	s_mov_b64 exec, s[20:21]
	v_cvt_pk_bf16_f32 v2, v3, s0
	v_lshlrev_b32_e32 v4, 4, v57
	v_lshl_add_u32 v4, v87, 1, v4
	ds_write_b16 v4, v2
	v_lshlrev_b32_e32 v2, 16, v28
	v_lshlrev_b32_e32 v12, 16, v38
	v_sub_f32_e32 v4, v12, v2
	v_fmac_f32_e32 v2, v4, v48
	v_cmp_lt_i32_e32 vcc, 63, v68
	s_mov_b64 s[20:21], exec
	s_and_b64 exec, exec, vcc
	s_cbranch_execz .Lb1s_t8
	v_mul_f32_e32 v3, 0xbfb8aa3b, v2
	v_exp_f32_e32 v3, v3
	v_cmp_gt_u32_e32 vcc, s40, v68
	v_add_f32_e32 v3, 1.0, v3
	v_rcp_f32_e32 v3, v3
	s_nop 0
	v_cndmask_b32_e32 v3, v3, v2, vcc

; __device__ __forceinline__ bf16_t f2bf(float f) { const __bf16 r = (__bf16)f; bf16_t u; __builtin_memcpy(&u, &r, 2); return u; }
; __device__ __forceinline__ float bf2f(bf16_t b) { return __uint_as_float(((unsigned)b) << 16); }
; __device__ __forceinline__ float sigmoidf_(float x) { return frcp(1.0f + __expf(-x)); }
; __device__ __forceinline__ void phase_b1(const P& p, const Ctx& c, int seg) {
;     ...
;         for (int e = c.tid; e < 16 * 288; e += 512) { const int row = e / 288, cc = e % 288, col = 4608 + cc;
;             const float cur = bf2f(P1[(size_t)(r0 + row) * P1W + col]);
;             float prev = 0.f; if (tl0 + row > 0) prev = bf2f(P1[(size_t)(r0 + row - 1) * P1W + col]); else if (seg > 0) prev = bf2f(PTr[(size_t)b * RW_SHIFT + col]);
;             const float pv = cur + p.rw_mu[col] * (prev - cur);
;             const float f = cc < 64 ? (1.0f - 2.0f / (1.0f + __expf(2.0f * pv)))   : (cc < 160 ? pv : sigmoidf_(pv));
;             XA[row * 296 + cc] = f2bf(f); }
.Lb1s_j8:
	s_mov_b64 exec, s[20:21]
	v_cvt_pk_bf16_f32 v2, v3, s0
	v_lshlrev_b32_e32 v4, 4, v58
	v_lshl_add_u32 v4, v88, 1, v4
	ds_write_b16 v4, v2
